# P7c v-axpy: byte transposes through LDS (ds_write_b128 + ds_read_b64_tr_b8, XOR-swizzled) instead of v_perm; lanes own whole output columns
# speedup vs baseline: 1.0250x; 1.0024x over previous
; __device__ __forceinline__ int fresh_lane() { int l; asm volatile("v_mbcnt_lo_u32_b32 %0, -1, 0\n\tv_mbcnt_hi_u32_b32 %0, -1, %0" : "=v"(l)); return l; }
; __device__ __forceinline__ unsigned xb_ld(unsigned* p)              { return __hip_atomic_load(p, __ATOMIC_RELAXED, __HIP_MEMORY_SCOPE_AGENT); }
; __device__ __forceinline__ SliceOwn slice_census(unsigned* bar, unsigned x) {
;     SliceOwn s; s.n_mine = 1u; s.vx = 0u; s.npop = 0u;
; #pragma unroll
;     for (unsigned j = 0; j < 16; ++j) { const unsigned c = (unsigned)__builtin_amdgcn_readfirstlane((int)xb_ld(&bar[XB_XCNT(j)])); if (c > 0u) { if (j < x) ++s.vx; ++s.npop; } if (j == x) s.n_mine = c > 0u ? c : 1u; }
;     if (s.npop == 0u) s.npop = 1u;
;     return s;
; }
; __device__ __forceinline__ void p7c_vaxpy(Frame& F, unsigned* bar, unsigned x, unsigned rank) {
;     const int lane = fresh_lane(), r = lane >> 3, seg = lane & 7;
;     const SliceOwn so = slice_census(bar, x);
;     const int gwl = (int)rank * NWAVES + F.wave, stride = (int)so.n_mine * NWAVES;
.LBB0_1082:
	s_or_b64 exec, exec, s[0:1]
	s_waitcnt vmcnt(31)
	v_mov_b32_e32 v157, 0
	s_waitcnt lgkmcnt(0)
	s_barrier
	v_mbcnt_lo_u32_b32 v6, -1, 0
	v_mbcnt_hi_u32_b32 v6, -1, v6
	global_load_dword v0, v157, s[66:67] offset:1024 sc1
	global_load_dword v2, v157, s[66:67] offset:1280 sc1
	v_readlane_b32 s4, v254, 36
	v_readlane_b32 s5, v254, 37
	v_readlane_b32 s6, v254, 40
	v_readlane_b32 s7, v254, 41
	v_readlane_b32 s8, v255, 5
	v_readlane_b32 s9, v255, 6
	v_readlane_b32 s10, v254, 46
	v_readlane_b32 s11, v254, 47
	v_ashrrev_i32_e32 v12, 3, v6
	v_readlane_b32 s12, v255, 9
	v_readlane_b32 s13, v255, 10
	s_mov_b32 s22, 0
	s_mov_b32 s25, 0x5040100
	s_mov_b32 s26, 0x7060302
	v_mov_b32_e32 v194, 7
	s_waitcnt vmcnt(1)
	v_readfirstlane_b32 s2, v0
	s_waitcnt vmcnt(0)
	v_readfirstlane_b32 s3, v2
	global_load_dword v2, v157, s[66:67] offset:1536 sc1
	global_load_dword v3, v157, s[66:67] offset:1792 sc1
	global_load_dword v4, v157, s[66:67] offset:2048 sc1
	global_load_dword v5, v157, s[66:67] offset:2304 sc1
	global_load_dword v7, v157, s[66:67] offset:2560 sc1
	global_load_dword v8, v157, s[66:67] offset:2816 sc1
	global_load_dword v9, v157, s[66:67] offset:3072 sc1
	global_load_dword v10, v157, s[66:67] offset:3328 sc1
	global_load_dword v13, v157, s[66:67] offset:3584 sc1
	global_load_dword v14, v157, s[66:67] offset:3840 sc1
	global_load_dword v15, v157, s[46:47] sc1
	global_load_dword v16, v157, s[48:49] sc1
	global_load_dword v17, v157, s[50:51] sc1
	global_load_dword v18, v157, s[52:53] sc1
	s_cmp_lg_u32 s2, 0
	s_cselect_b64 s[0:1], -1, 0
	v_cndmask_b32_e64 v0, 0, 1, s[0:1]
	s_and_b64 s[0:1], s[4:5], s[0:1]
	s_max_u32 s2, s2, 1
	v_cndmask_b32_e64 v1, 0, 1, s[0:1]
	s_and_b64 s[0:1], s[70:71], exec
	s_cselect_b32 s2, s2, 1
	s_cmp_lg_u32 s3, 0
	s_cselect_b64 vcc, -1, 0
	v_addc_co_u32_e64 v0, s[0:1], 0, v0, vcc
	v_readlane_b32 s0, v254, 38
	v_readlane_b32 s1, v254, 39
	s_and_b64 s[0:1], s[0:1], vcc
	s_max_u32 s3, s3, 1
	v_cndmask_b32_e64 v11, 0, 1, s[0:1]
	s_and_b64 s[0:1], s[72:73], exec
	s_cselect_b32 s2, s3, s2
	v_add_u32_e32 v1, v11, v1
	s_waitcnt vmcnt(13)
	v_readfirstlane_b32 s4, v2
	s_cmp_lg_u32 s4, 0
	s_cselect_b64 s[0:1], -1, 0
	v_cndmask_b32_e64 v2, 0, 1, s[0:1]
	s_and_b64 s[0:1], s[6:7], s[0:1]
	s_max_u32 s4, s4, 1
	s_waitcnt vmcnt(12)
	v_readfirstlane_b32 s3, v3
	v_cndmask_b32_e64 v3, 0, 1, s[0:1]
	s_and_b64 s[0:1], s[74:75], exec
	s_cselect_b32 s2, s4, s2
	s_cmp_lg_u32 s3, 0
	s_cselect_b64 vcc, -1, 0
	v_addc_co_u32_e64 v0, s[0:1], v0, v2, vcc
	v_readlane_b32 s0, v255, 3
	v_readlane_b32 s1, v255, 4
	s_and_b64 s[0:1], s[0:1], vcc
	s_max_u32 s3, s3, 1
	s_waitcnt vmcnt(11)
	v_readfirstlane_b32 s5, v4
	v_cndmask_b32_e64 v2, 0, 1, s[0:1]
	s_and_b64 s[0:1], s[76:77], exec
	s_cselect_b32 s2, s3, s2
	s_cmp_lg_u32 s5, 0
	s_cselect_b64 s[0:1], -1, 0
	v_cndmask_b32_e64 v4, 0, 1, s[0:1]
	s_and_b64 s[0:1], s[8:9], s[0:1]
	v_add_u32_e32 v1, v1, v3
	s_max_u32 s5, s5, 1
	s_waitcnt vmcnt(10)
	v_readfirstlane_b32 s4, v5
	v_add_u32_e32 v1, v1, v2
	v_cndmask_b32_e64 v2, 0, 1, s[0:1]
	s_and_b64 s[0:1], s[78:79], exec
	s_cselect_b32 s2, s5, s2
	s_cmp_lg_u32 s4, 0
	s_cselect_b64 vcc, -1, 0
	v_addc_co_u32_e64 v0, s[0:1], v0, v4, vcc
	v_readlane_b32 s0, v255, 1
	v_readlane_b32 s1, v255, 2
	s_max_u32 s4, s4, 1
	s_and_b64 s[0:1], s[0:1], vcc
	s_waitcnt vmcnt(9)
	v_readfirstlane_b32 s6, v7
	v_add_u32_e32 v1, v1, v2
	v_cndmask_b32_e64 v2, 0, 1, s[0:1]
	s_and_b64 s[0:1], s[80:81], exec
	s_cselect_b32 s2, s4, s2
	s_cmp_lg_u32 s6, 0
	s_cselect_b64 s[0:1], -1, 0
	v_add_u32_e32 v1, v1, v2
	v_cndmask_b32_e64 v2, 0, 1, s[0:1]
	s_max_u32 s4, s6, 1
	s_and_b64 s[0:1], s[10:11], s[0:1]
	s_waitcnt vmcnt(8)
	v_readfirstlane_b32 s7, v8
	v_cndmask_b32_e64 v3, 0, 1, s[0:1]
	s_and_b64 s[0:1], s[84:85], exec
	s_cselect_b32 s2, s4, s2
	s_cmp_lg_u32 s7, 0
	s_cselect_b64 vcc, -1, 0
	v_addc_co_u32_e64 v0, s[0:1], v0, v2, vcc
	v_readlane_b32 s0, v254, 44
	v_readlane_b32 s1, v254, 45
	s_max_u32 s4, s7, 1
	s_and_b64 s[0:1], s[0:1], vcc
	s_waitcnt vmcnt(7)
	v_readfirstlane_b32 s3, v9
	v_cndmask_b32_e64 v2, 0, 1, s[0:1]
	s_and_b64 s[0:1], s[86:87], exec
	s_cselect_b32 s2, s4, s2
	s_cmp_lg_u32 s3, 0
	v_readlane_b32 s4, v254, 42
	v_add_u32_e32 v1, v1, v3
	s_cselect_b64 s[0:1], -1, 0
	v_readlane_b32 s5, v254, 43
	v_add_u32_e32 v1, v1, v2
	v_cndmask_b32_e64 v2, 0, 1, s[0:1]
	s_max_u32 s3, s3, 1
	s_and_b64 s[0:1], s[4:5], s[0:1]
	s_waitcnt vmcnt(6)
	v_readfirstlane_b32 s8, v10
	v_cndmask_b32_e64 v3, 0, 1, s[0:1]
	s_and_b64 s[0:1], s[88:89], exec
	s_cselect_b32 s2, s3, s2
	s_cmp_lg_u32 s8, 0
	s_cselect_b64 vcc, -1, 0
	v_addc_co_u32_e64 v0, s[0:1], v0, v2, vcc
	v_readlane_b32 s0, v254, 34
	v_readlane_b32 s1, v254, 35
	s_and_b64 s[0:1], s[0:1], vcc
	s_max_u32 s3, s8, 1
	v_cndmask_b32_e64 v2, 0, 1, s[0:1]
	s_and_b64 s[0:1], s[90:91], exec
	s_cselect_b32 s2, s3, s2
	s_waitcnt vmcnt(5)
	v_readfirstlane_b32 s3, v13
	s_cmp_lg_u32 s3, 0
	v_readlane_b32 s4, v255, 41
	v_add_u32_e32 v1, v1, v3
	s_cselect_b64 s[0:1], -1, 0
	v_readlane_b32 s5, v255, 42
	v_add_u32_e32 v1, v1, v2
	v_cndmask_b32_e64 v2, 0, 1, s[0:1]
	s_and_b64 s[0:1], s[4:5], s[0:1]
	s_max_u32 s3, s3, 1
	v_cndmask_b32_e64 v3, 0, 1, s[0:1]
	s_and_b64 s[0:1], s[92:93], exec
	s_cselect_b32 s2, s3, s2
	s_waitcnt vmcnt(4)
	v_readfirstlane_b32 s3, v14
	s_cmp_lg_u32 s3, 0
	s_cselect_b64 vcc, -1, 0
	v_addc_co_u32_e64 v0, s[0:1], v0, v2, vcc
	v_readlane_b32 s0, v255, 43
	v_readlane_b32 s1, v255, 44
	s_and_b64 s[0:1], s[0:1], vcc
	s_max_u32 s3, s3, 1
	v_cndmask_b32_e64 v2, 0, 1, s[0:1]
	s_and_b64 s[0:1], s[94:95], exec
	s_cselect_b32 s2, s3, s2
	s_waitcnt vmcnt(3)
; __device__ __forceinline__ int fresh_lane() { int l; asm volatile("v_mbcnt_lo_u32_b32 %0, -1, 0\n\tv_mbcnt_hi_u32_b32 %0, -1, %0" : "=v"(l)); return l; }
; __device__ __forceinline__ void p7c_vaxpy(Frame& F, unsigned* bar, unsigned x, unsigned rank) {
;     const int lane = fresh_lane(), r = lane >> 3, seg = lane & 7;
;     const SliceOwn so = slice_census(bar, x);
;     const int gwl = (int)rank * NWAVES + F.wave, stride = (int)so.n_mine * NWAVES;
;     const unsigned char* RE16b = F.ws + WS_RE16; const unsigned char* CQb = F.ws + WS_CQ; const float* SCQ = (const float*)(F.ws + WS_SCQ);
;     float* SS3 = (float*)(F.ws + WS_SS3); bf16* X2Bw = (bf16*)(F.ws + WS_X2B);
; #pragma unroll 1
;     for (int pass = 0; pass < 16; ++pass) {
;         const int hs = (2 * (int)so.vx + pass) & 15; if ((unsigned)(hs >> 1) % so.npop != so.vx) continue;
;         const unsigned char* Vb = F.ws + WS_V + (size_t)hs * (16384 * 128) + 16 * seg;
;         const unsigned char* rp0 = RE16b + r * 32; const unsigned char* cp0 = CQb + r * 16;
	v_readfirstlane_b32 s3, v15
	s_cmp_lg_u32 s3, 0
	v_readlane_b32 s4, v255, 45
	v_add_u32_e32 v1, v1, v3
	s_cselect_b64 s[0:1], -1, 0
	v_readlane_b32 s5, v255, 46
	v_add_u32_e32 v1, v1, v2
	v_cndmask_b32_e64 v2, 0, 1, s[0:1]
	s_and_b64 s[0:1], s[4:5], s[0:1]
	v_cndmask_b32_e64 v3, 0, 1, s[0:1]
	v_readlane_b32 s0, v254, 7
	s_max_u32 s3, s3, 1
	v_readlane_b32 s1, v254, 8
	s_and_b64 s[0:1], s[0:1], exec
	s_cselect_b32 s2, s3, s2
	s_waitcnt vmcnt(2)
	v_readfirstlane_b32 s3, v16
	s_cmp_lg_u32 s3, 0
	s_cselect_b64 vcc, -1, 0
	v_addc_co_u32_e64 v0, s[0:1], v0, v2, vcc
	v_readlane_b32 s0, v255, 47
	v_readlane_b32 s1, v255, 48
	s_and_b64 s[0:1], s[0:1], vcc
	s_max_u32 s3, s3, 1
	v_cndmask_b32_e64 v2, 0, 1, s[0:1]
	v_readlane_b32 s0, v255, 39
	v_readlane_b32 s1, v255, 40
	s_and_b64 s[0:1], s[0:1], exec
	s_cselect_b32 s2, s3, s2
	s_waitcnt vmcnt(1)
	v_readfirstlane_b32 s3, v17
	s_cmp_lg_u32 s3, 0
	v_readlane_b32 s4, v254, 51
	v_add_u32_e32 v1, v1, v3
	s_cselect_b64 s[0:1], -1, 0
	v_readlane_b32 s5, v254, 52
	v_add_u32_e32 v1, v1, v2
	v_cndmask_b32_e64 v2, 0, 1, s[0:1]
	s_and_b64 s[0:1], s[4:5], s[0:1]
	v_cndmask_b32_e64 v3, 0, 1, s[0:1]
	v_readlane_b32 s0, v255, 37
	s_max_u32 s3, s3, 1
	v_readlane_b32 s1, v255, 38
	s_and_b64 s[0:1], s[0:1], exec
	s_waitcnt vmcnt(0)
	v_readfirstlane_b32 s0, v18
	s_cselect_b32 s2, s3, s2
	s_cmp_lg_u32 s0, 0
	s_cselect_b64 vcc, -1, 0
	v_addc_co_u32_e32 v0, vcc, v0, v2, vcc
	s_max_u32 s3, s0, 1
	s_and_b64 s[0:1], s[4:5], exec
	v_max_u32_e32 v191, 1, v0
	v_lshlrev_b32_e32 v0, 4, v6
	s_cselect_b32 s24, s3, s2
	s_lshl_b32 s0, s33, 3
	v_and_b32_e32 v156, 0x70, v0
	v_lshlrev_b32_e32 v0, 5, v12
	v_add_u32_e32 v190, v1, v3
	s_add_i32 s0, s0, s96
	s_lshl_b32 s23, s24, 3
	v_ashrrev_i32_e32 v1, 31, v0
	s_add_u32 s2, s66, 0x1de00000
	v_lshl_add_u64 v[158:159], s[42:43], 0, v[0:1]
	v_lshlrev_b32_e32 v0, 4, v12
	s_addc_u32 s3, s67, 0
	v_ashrrev_i32_e32 v1, 31, v0
	s_min_i32 s6, s0, 0x5fff
	v_lshl_add_u64 v[0:1], s[66:67], 0, v[0:1]
	s_mov_b64 s[4:5], 0x1da00000
	s_ashr_i32 s7, s6, 31
	v_lshl_add_u64 v[160:161], v[0:1], 0, s[4:5]
	s_lshl_b64 s[4:5], s[6:7], 8
	v_lshl_add_u64 v[162:163], v[158:159], 0, s[4:5]
	s_lshl_b64 s[4:5], s[6:7], 7
	v_lshl_add_u64 v[164:165], v[160:161], 0, s[4:5]
	s_lshl_b64 s[4:5], s[6:7], 2
	s_add_u32 s4, s54, s4
	s_addc_u32 s5, s55, s5
	s_lshl_b64 s[6:7], s[6:7], 12
	s_add_u32 s6, s40, s6
	s_addc_u32 s7, s41, s7
	s_add_i32 s1, s23, s0
	s_min_i32 s8, s1, 0x5fff
	v_and_b32_e32 v230, 0x30, v6
	v_and_b32_e32 v232, 15, v6
	v_lshlrev_b32_e32 v230, 2, v230
	v_lshl_add_u32 v230, v232, 1, v230
	v_and_b32_e32 v232, 1, v6
	v_mad_u32_u24 v0, v232, 30, v230
	v_mov_b32_e32 v1, v157
	s_ashr_i32 s9, s8, 31
	v_lshl_add_u64 v[2:3], s[6:7], 0, v[0:1]
	s_lshl_b64 s[6:7], s[8:9], 8
	v_lshl_add_u64 v[168:169], v[158:159], 0, s[6:7]
	s_lshl_b64 s[6:7], s[8:9], 7
	v_lshl_add_u64 v[170:171], v[160:161], 0, s[6:7]
	s_lshl_b64 s[6:7], s[8:9], 2
	s_add_u32 s6, s54, s6
	v_mov_b32_e32 v4, 0
	s_addc_u32 s7, s55, s7
	s_lshl_b64 s[8:9], s[8:9], 12
	v_ashrrev_i32_e32 v5, 31, v4
	s_add_u32 s8, s40, s8
	v_lshlrev_b64 v[4:5], 1, v[4:5]
	s_addc_u32 s9, s41, s9
	v_lshl_add_u64 v[166:167], v[2:3], 0, v[4:5]
	v_lshl_add_u64 v[2:3], s[8:9], 0, v[0:1]
	v_lshl_add_u64 v[0:1], s[40:41], 0, v[0:1]
	v_lshl_add_u64 v[174:175], v[0:1], 0, v[4:5]
	v_cvt_f32_u32_e32 v1, v191
	v_and_b32_e32 v0, 32, v6
	v_cmp_eq_u32_e64 s[36:37], 0, v0
	v_and_b32_e32 v0, 16, v6
	v_cmp_eq_u32_e64 s[38:39], 0, v0
	v_rcp_iflag_f32_e32 v0, v1
	s_cmpk_lt_i32 s0, 0x6000
	s_cselect_b64 s[8:9], -1, 0
	s_ashr_i32 s1, s0, 31
	v_mul_f32_e32 v0, 0x4f7ffffe, v0
	v_cvt_u32_f32_e32 v0, v0
	s_lshl_b32 s10, s24, 4
	v_and_b32_e32 v1, 8, v6
	v_lshl_add_u64 v[176:177], s[12:13], 0, v[156:157]
	s_lshl_b64 s[12:13], s[0:1], 6
	v_cmp_eq_u32_e64 s[40:41], 0, v1
	v_sub_u32_e32 v1, 0, v191
	s_add_u32 s11, s66, s12
	v_mul_lo_u32 v1, v1, v0
	s_addc_u32 s13, s67, s13
	v_mul_hi_u32 v1, v0, v1
	s_add_u32 s12, s11, 0x1de00000
	v_add_u32_e32 v193, v0, v1
	s_addc_u32 s13, s13, 0
	s_lshl_b64 s[16:17], s[0:1], 12
	v_and_b32_e32 v230, 0x30, v6
	v_and_b32_e32 v232, 15, v6
	v_lshlrev_b32_e32 v230, 2, v230
	v_lshl_add_u32 v230, v232, 1, v230
	v_and_b32_e32 v232, 1, v6
	v_mad_u32_u24 v0, v232, 30, v230
	v_or_b32_e32 v0, s16, v0
	v_mov_b32_e32 v1, s17
	v_lshl_add_u64 v[0:1], v[0:1], 0, v[4:5]
	v_lshlrev_b32_e32 v192, 1, v190
	s_ashr_i32 s11, s10, 31
	v_lshl_add_u64 v[0:1], s[66:67], 0, v[0:1]
	s_mov_b64 s[16:17], 0x16800000
	v_lshl_add_u64 v[172:173], v[2:3], 0, v[4:5]
	v_cmp_eq_u32_e64 s[42:43], 0, v6
	v_readlane_b32 s97, v254, 23
	v_and_b32_e32 v230, 1, v6
	v_cmp_eq_u32_e64 s[44:45], 0, v230
	s_nop 1
	s_lshl_b32 s97, s97, 14
	v_bfe_u32 v230, v6, 4, 1
	v_lshlrev_b32_e32 v230, 2, v230
	v_and_b32_e32 v232, 7, v6
	v_xor_b32_e32 v230, v230, v232
	v_and_b32_e32 v232, 0x38, v6
	v_lshlrev_b32_e32 v232, 4, v232
	v_lshl_add_u32 v230, v230, 4, v232
	v_add_u32_e32 v230, s97, v230
	v_xor_b32_e32 v208, 0, v230
	v_xor_b32_e32 v209, 16, v230
	v_xor_b32_e32 v210, 32, v230
	v_xor_b32_e32 v211, 48, v230
	v_bfe_u32 v230, v6, 1, 2
	v_lshrrev_b32_e32 v232, 4, v6
	v_lshlrev_b32_e32 v233, 10, v230
	v_lshl_add_u32 v233, v232, 8, v233
	v_and_b32_e32 v232, 1, v232
	v_lshl_or_b32 v230, v232, 2, v230
	v_bfe_u32 v232, v6, 3, 1
	v_lshl_add_u32 v233, v232, 7, v233
	v_and_b32_e32 v232, 1, v6
	v_lshl_add_u32 v233, v232, 3, v233
	v_add_u32_e32 v233, s97, v233
	v_xor_b32_e32 v232, 0, v230
	v_lshl_add_u32 v212, v232, 4, v233
	v_xor_b32_e32 v232, 1, v230
	v_lshl_add_u32 v213, v232, 4, v233
	v_xor_b32_e32 v232, 2, v230
	v_lshl_add_u32 v214, v232, 4, v233
	v_xor_b32_e32 v232, 3, v230
	v_lshl_add_u32 v215, v232, 4, v233
	v_xor_b32_e32 v232, 4, v230
	v_lshl_add_u32 v216, v232, 4, v233
	v_xor_b32_e32 v232, 5, v230
	v_lshl_add_u32 v217, v232, 4, v233
	v_xor_b32_e32 v232, 6, v230
	v_lshl_add_u32 v218, v232, 4, v233
	v_xor_b32_e32 v232, 7, v230
	v_lshl_add_u32 v219, v232, 4, v233
	s_mul_i32 s24, s24, 24
	s_lshl_b64 s[14:15], s[10:11], 6
	v_lshl_add_u64 v[178:179], v[0:1], 0, s[16:17]
	s_lshl_b64 s[16:17], s[10:11], 12
	s_mov_b32 s1, 0x5010400
	s_mov_b32 s11, 0x7030602
	v_mov_b32_e32 v195, v192
	s_branch .LBB0_1084

.LBB0_1089:
	s_add_i32 s27, s20, s10
	s_min_i32 s18, s27, 0x5fff
	s_ashr_i32 s19, s18, 31
	s_waitcnt vmcnt(23)
	v_mov_b64_e32 v[154:155], v[2:3]
	s_lshl_b64 s[28:29], s[18:19], 8
	v_mov_b64_e32 v[152:153], v[0:1]
	v_lshl_add_u64 v[0:1], v[158:159], 0, s[28:29]
	s_lshl_b64 s[28:29], s[18:19], 7
	global_load_dwordx4 v[144:147], v[0:1], off offset:16
	global_load_dwordx4 v[148:151], v[0:1], off
	v_lshl_add_u64 v[0:1], v[160:161], 0, s[28:29]
	s_lshl_b64 s[28:29], s[18:19], 2
	s_add_u32 s28, s54, s28
	s_addc_u32 s29, s55, s29
	s_lshl_b64 s[18:19], s[18:19], 12
	s_waitcnt vmcnt(20)
	v_mov_b32_e32 v206, v197
	v_mov_b32_e32 v207, v196
	v_lshl_add_u64 v[80:81], v[182:183], 0, s[18:19]
	global_load_dwordx4 v[0:3], v[0:1], off
	s_nop 0
	global_load_dword v196, v157, s[28:29]
	global_load_dword v197, v[80:81], off
	s_setprio 3
	v_lshlrev_b32_e32 v80, 7, v76
	v_and_b32_e32 v156, 0x7fff80, v80
	v_lshl_add_u64 v[80:81], v[180:181], 0, v[156:157]
	v_lshlrev_b32_sdwa v156, v194, v76 dst_sel:DWORD dst_unused:UNUSED_PAD src0_sel:DWORD src1_sel:WORD_1
	v_lshlrev_b32_e32 v76, 7, v77
	v_lshl_add_u64 v[82:83], v[180:181], 0, v[156:157]
	v_and_b32_e32 v156, 0x7fff80, v76
	global_load_dwordx4 v[128:131], v[80:81], off
	global_load_dwordx4 v[132:135], v[82:83], off
	v_lshl_add_u64 v[80:81], v[180:181], 0, v[156:157]
	v_lshlrev_b32_sdwa v156, v194, v77 dst_sel:DWORD dst_unused:UNUSED_PAD src0_sel:DWORD src1_sel:WORD_1
	v_lshl_add_u64 v[76:77], v[180:181], 0, v[156:157]
	global_load_dwordx4 v[136:139], v[80:81], off
	global_load_dwordx4 v[140:143], v[76:77], off
	v_lshlrev_b32_e32 v76, 7, v78
	v_and_b32_e32 v156, 0x7fff80, v76
	v_lshl_add_u64 v[76:77], v[180:181], 0, v[156:157]
	v_lshlrev_b32_sdwa v156, v194, v78 dst_sel:DWORD dst_unused:UNUSED_PAD src0_sel:DWORD src1_sel:WORD_1
	v_lshl_add_u64 v[80:81], v[180:181], 0, v[156:157]
	global_load_dwordx4 v[112:115], v[76:77], off
	global_load_dwordx4 v[116:119], v[80:81], off
	v_lshlrev_b32_e32 v76, 7, v79
	v_and_b32_e32 v156, 0x7fff80, v76
	v_lshl_add_u64 v[76:77], v[180:181], 0, v[156:157]
	v_lshlrev_b32_sdwa v156, v194, v79 dst_sel:DWORD dst_unused:UNUSED_PAD src0_sel:DWORD src1_sel:WORD_1
	v_lshl_add_u64 v[78:79], v[180:181], 0, v[156:157]
	global_load_dwordx4 v[120:123], v[76:77], off
	global_load_dwordx4 v[124:127], v[78:79], off
	v_lshlrev_b32_e32 v76, 7, v64
	v_and_b32_e32 v156, 0x7fff80, v76
	v_lshl_add_u64 v[76:77], v[180:181], 0, v[156:157]
	v_lshlrev_b32_sdwa v156, v194, v64 dst_sel:DWORD dst_unused:UNUSED_PAD src0_sel:DWORD src1_sel:WORD_1
	v_lshlrev_b32_e32 v64, 7, v65
	v_lshl_add_u64 v[78:79], v[180:181], 0, v[156:157]
	v_and_b32_e32 v156, 0x7fff80, v64
	global_load_dwordx4 v[96:99], v[76:77], off
	global_load_dwordx4 v[100:103], v[78:79], off
	v_lshl_add_u64 v[76:77], v[180:181], 0, v[156:157]
	v_lshlrev_b32_sdwa v156, v194, v65 dst_sel:DWORD dst_unused:UNUSED_PAD src0_sel:DWORD src1_sel:WORD_1
	v_lshl_add_u64 v[64:65], v[180:181], 0, v[156:157]
	global_load_dwordx4 v[104:107], v[76:77], off
	global_load_dwordx4 v[108:111], v[64:65], off
	v_lshlrev_b32_e32 v64, 7, v66
	v_and_b32_e32 v156, 0x7fff80, v64
	v_lshl_add_u64 v[64:65], v[180:181], 0, v[156:157]
	v_lshlrev_b32_sdwa v156, v194, v66 dst_sel:DWORD dst_unused:UNUSED_PAD src0_sel:DWORD src1_sel:WORD_1
	v_lshl_add_u64 v[76:77], v[180:181], 0, v[156:157]
	global_load_dwordx4 v[80:83], v[64:65], off
	global_load_dwordx4 v[84:87], v[76:77], off
	v_lshlrev_b32_e32 v64, 7, v67
	v_and_b32_e32 v156, 0x7fff80, v64
	v_lshl_add_u64 v[64:65], v[180:181], 0, v[156:157]
	v_lshlrev_b32_sdwa v156, v194, v67 dst_sel:DWORD dst_unused:UNUSED_PAD src0_sel:DWORD src1_sel:WORD_1
	v_lshl_add_u64 v[66:67], v[180:181], 0, v[156:157]
	global_load_dwordx4 v[88:91], v[64:65], off
	global_load_dwordx4 v[92:95], v[66:67], off
	s_setprio 0
	v_mov_b32_dpp v230, v152 row_ror:8 row_mask:0xf bank_mask:0xf
	v_cndmask_b32_e64 v220, v230, v152, s[40:41]
	v_cndmask_b32_e64 v224, v152, v230, s[40:41]
	v_mov_b32_dpp v230, v153 row_ror:8 row_mask:0xf bank_mask:0xf
	v_cndmask_b32_e64 v221, v230, v153, s[40:41]
	v_cndmask_b32_e64 v225, v153, v230, s[40:41]
	v_mov_b32_dpp v230, v154 row_ror:8 row_mask:0xf bank_mask:0xf
	v_cndmask_b32_e64 v222, v230, v154, s[40:41]
	v_cndmask_b32_e64 v226, v154, v230, s[40:41]
	v_mov_b32_dpp v230, v155 row_ror:8 row_mask:0xf bank_mask:0xf
	v_cndmask_b32_e64 v223, v230, v155, s[40:41]
	v_cndmask_b32_e64 v227, v155, v230, s[40:41]
	s_waitcnt vmcnt(33)
	ds_write_b128 v208, v[48:51]
	ds_write_b128 v209, v[52:55] offset:1024
	ds_write_b128 v210, v[68:71] offset:2048
	ds_write_b128 v211, v[72:75] offset:3072
	ds_read_b64_tr_b8 v[240:241], v212
	ds_read_b64_tr_b8 v[242:243], v213
	ds_read_b64_tr_b8 v[244:245], v214
	ds_read_b64_tr_b8 v[246:247], v215
	ds_read_b64_tr_b8 v[248:249], v216
	ds_read_b64_tr_b8 v[250:251], v217
	ds_read_b64_tr_b8 v[252:253], v218
	ds_read_b64_tr_b8 v[228:229], v219
	s_waitcnt lgkmcnt(4)
	s_waitcnt vmcnt(29)
	ds_write_b128 v208, v[32:35] offset:4096
	ds_write_b128 v209, v[36:39] offset:5120
	ds_write_b128 v210, v[56:59] offset:6144
	ds_write_b128 v211, v[60:63] offset:7168
	ds_read_b64_tr_b8 v[48:49], v212 offset:4096
	ds_read_b64_tr_b8 v[50:51], v213 offset:4096
	ds_read_b64_tr_b8 v[52:53], v214 offset:4096
	ds_read_b64_tr_b8 v[54:55], v215 offset:4096
	v_dot4_i32_i8 v232, v240, v220, 0
	v_dot4_i32_i8 v233, v242, v220, 0
	v_dot4_i32_i8 v234, v244, v220, 0
	v_dot4_i32_i8 v235, v246, v220, 0
	v_dot4_i32_i8 v232, v241, v224, v232
	v_dot4_i32_i8 v233, v243, v224, v233
	v_dot4_i32_i8 v234, v245, v224, v234
	v_dot4_i32_i8 v235, v247, v224, v235
	s_waitcnt lgkmcnt(8)
	ds_read_b64_tr_b8 v[240:241], v216 offset:4096
	ds_read_b64_tr_b8 v[242:243], v217 offset:4096
	ds_read_b64_tr_b8 v[244:245], v218 offset:4096
	ds_read_b64_tr_b8 v[246:247], v219 offset:4096
	v_dot4_i32_i8 v236, v248, v220, 0
	v_dot4_i32_i8 v237, v250, v220, 0
	v_dot4_i32_i8 v238, v252, v220, 0
	v_dot4_i32_i8 v239, v228, v220, 0
	v_dot4_i32_i8 v236, v249, v224, v236
	v_dot4_i32_i8 v237, v251, v224, v237
	v_dot4_i32_i8 v238, v253, v224, v238
	v_dot4_i32_i8 v239, v229, v224, v239
	s_waitcnt lgkmcnt(4)
	s_waitcnt vmcnt(25)
	ds_write_b128 v208, v[16:19] offset:8192
	ds_write_b128 v209, v[20:23] offset:9216
	ds_write_b128 v210, v[40:43] offset:10240
	ds_write_b128 v211, v[44:47] offset:11264
	ds_read_b64_tr_b8 v[248:249], v212 offset:8192
	ds_read_b64_tr_b8 v[250:251], v213 offset:8192
	ds_read_b64_tr_b8 v[252:253], v214 offset:8192
	ds_read_b64_tr_b8 v[228:229], v215 offset:8192
	v_dot4_i32_i8 v232, v48, v221, v232
	v_dot4_i32_i8 v233, v50, v221, v233
	v_dot4_i32_i8 v234, v52, v221, v234
	v_dot4_i32_i8 v235, v54, v221, v235
	v_dot4_i32_i8 v232, v49, v225, v232
	v_dot4_i32_i8 v233, v51, v225, v233
	v_dot4_i32_i8 v234, v53, v225, v234
	v_dot4_i32_i8 v235, v55, v225, v235
	s_waitcnt lgkmcnt(8)
	ds_read_b64_tr_b8 v[48:49], v216 offset:8192
	ds_read_b64_tr_b8 v[50:51], v217 offset:8192
	ds_read_b64_tr_b8 v[52:53], v218 offset:8192
	ds_read_b64_tr_b8 v[54:55], v219 offset:8192
	v_dot4_i32_i8 v236, v240, v221, v236
	v_dot4_i32_i8 v237, v242, v221, v237
	v_dot4_i32_i8 v238, v244, v221, v238
	v_dot4_i32_i8 v239, v246, v221, v239
	v_dot4_i32_i8 v236, v241, v225, v236
	v_dot4_i32_i8 v237, v243, v225, v237
	v_dot4_i32_i8 v238, v245, v225, v238
	v_dot4_i32_i8 v239, v247, v225, v239
	s_waitcnt lgkmcnt(4)
	s_waitcnt vmcnt(21)
	ds_write_b128 v208, v[8:11] offset:12288
	ds_write_b128 v209, v[12:15] offset:13312
	ds_write_b128 v210, v[24:27] offset:14336
	ds_write_b128 v211, v[28:31] offset:15360
	ds_read_b64_tr_b8 v[240:241], v212 offset:12288
	ds_read_b64_tr_b8 v[242:243], v213 offset:12288
	ds_read_b64_tr_b8 v[244:245], v214 offset:12288
	ds_read_b64_tr_b8 v[246:247], v215 offset:12288
	v_dot4_i32_i8 v232, v248, v222, v232
	v_dot4_i32_i8 v233, v250, v222, v233
	v_dot4_i32_i8 v234, v252, v222, v234
	v_dot4_i32_i8 v235, v228, v222, v235
	v_dot4_i32_i8 v232, v249, v226, v232
	v_dot4_i32_i8 v233, v251, v226, v233
	v_dot4_i32_i8 v234, v253, v226, v234
	v_dot4_i32_i8 v235, v229, v226, v235
	s_waitcnt lgkmcnt(8)
	ds_read_b64_tr_b8 v[248:249], v216 offset:12288
	ds_read_b64_tr_b8 v[250:251], v217 offset:12288
	ds_read_b64_tr_b8 v[252:253], v218 offset:12288
	ds_read_b64_tr_b8 v[228:229], v219 offset:12288
	v_dot4_i32_i8 v236, v48, v222, v236
	v_dot4_i32_i8 v237, v50, v222, v237
	v_dot4_i32_i8 v238, v52, v222, v238
	v_dot4_i32_i8 v239, v54, v222, v239
	v_dot4_i32_i8 v236, v49, v226, v236
	v_dot4_i32_i8 v237, v51, v226, v237
	v_dot4_i32_i8 v238, v53, v226, v238
	v_dot4_i32_i8 v239, v55, v226, v239
	s_waitcnt lgkmcnt(4)
	v_dot4_i32_i8 v232, v240, v223, v232
	v_dot4_i32_i8 v233, v242, v223, v233
	v_dot4_i32_i8 v234, v244, v223, v234
	v_dot4_i32_i8 v235, v246, v223, v235
	v_dot4_i32_i8 v232, v241, v227, v232
	v_dot4_i32_i8 v233, v243, v227, v233
	v_dot4_i32_i8 v234, v245, v227, v234
	v_dot4_i32_i8 v235, v247, v227, v235
	s_waitcnt lgkmcnt(0)
	v_dot4_i32_i8 v236, v248, v223, v236
	v_dot4_i32_i8 v237, v250, v223, v237
	v_dot4_i32_i8 v238, v252, v223, v238
	v_dot4_i32_i8 v239, v228, v223, v239
	v_dot4_i32_i8 v236, v249, v227, v236
	v_dot4_i32_i8 v237, v251, v227, v237
	v_dot4_i32_i8 v238, v253, v227, v238
	v_dot4_i32_i8 v239, v229, v227, v239
	s_nop 2
	v_permlane32_swap_b32_e32 v232, v236
	v_permlane32_swap_b32_e32 v233, v237
	v_permlane32_swap_b32_e32 v234, v238
	v_permlane32_swap_b32_e32 v235, v239
	v_add_u32_e32 v232, v232, v236
	v_add_u32_e32 v233, v233, v237
	v_add_u32_e32 v234, v234, v238
	v_add_u32_e32 v235, v235, v239
	s_nop 1
	v_permlane16_swap_b32_e32 v232, v234
	v_permlane16_swap_b32_e32 v233, v235
	v_add_u32_e32 v232, v232, v234
	v_add_u32_e32 v233, v233, v235
	s_nop 1
	v_mov_b32_dpp v234, v232 quad_perm:[1,0,3,2] row_mask:0xf bank_mask:0xf
	v_mov_b32_dpp v235, v233 quad_perm:[1,0,3,2] row_mask:0xf bank_mask:0xf
	v_cndmask_b32_e64 v236, v235, v232, s[44:45]
	v_cndmask_b32_e64 v237, v233, v234, s[44:45]
	v_cvt_f32_i32_e32 v236, v236
	v_cvt_f32_i32_e32 v237, v237
	v_lshlrev_b32_e32 v238, 16, v206
	v_and_b32_e32 v239, 0xffff0000, v206
	v_fmac_f32_e32 v238, v207, v236
	v_fmac_f32_e32 v239, v207, v237
	v_mul_f32_e32 v240, v239, v239
	v_fmac_f32_e32 v240, v238, v238
	v_cvt_pk_bf16_f32 v244, v238, v239
	global_store_dword v[188:189], v244, off
	s_nop 1
	v_add_f32_dpp v240, v240, v240 quad_perm:[1,0,3,2] row_mask:0xf bank_mask:0xf
	s_nop 1
	v_add_f32_dpp v240, v240, v240 quad_perm:[2,3,0,1] row_mask:0xf bank_mask:0xf
	s_nop 1
	v_add_f32_dpp v240, v240, v240 row_half_mirror row_mask:0xf bank_mask:0xf
	s_nop 1
	v_add_f32_dpp v240, v240, v240 row_mirror row_mask:0xf bank_mask:0xf
	v_mov_b32_e32 v242, v240
	s_nop 1
	v_permlane16_swap_b32_e32 v240, v242
	v_add_f32_e32 v240, v240, v242
	v_mov_b32_e32 v242, v240
	s_nop 1
	v_permlane32_swap_b32_e32 v240, v242
	v_add_f32_e32 v240, v240, v242
	s_and_saveexec_b64 s[18:19], s[42:43]
	s_cbranch_execz .LBB0_1091
	global_store_dword v[186:187], v240, off
.LBB0_1091:
	s_or_b64 exec, exec, s[18:19]
	s_add_i32 s18, s24, s20
	s_min_i32 s18, s18, 0x5fff
	s_ashr_i32 s19, s18, 31
	s_lshl_b64 s[28:29], s[18:19], 8
	s_waitcnt lgkmcnt(0)
	v_lshl_add_u64 v[8:9], v[158:159], 0, s[28:29]
	s_lshl_b64 s[28:29], s[18:19], 7
	global_load_dwordx4 v[64:67], v[8:9], off offset:16
	global_load_dwordx4 v[76:79], v[8:9], off
	v_lshl_add_u64 v[8:9], v[160:161], 0, s[28:29]
	s_lshl_b64 s[28:29], s[18:19], 2
	s_add_u32 s28, s54, s28
	s_addc_u32 s29, s55, s29
	s_lshl_b64 s[18:19], s[18:19], 12
	v_lshl_add_u64 v[10:11], v[182:183], 0, s[18:19]
	global_load_dwordx4 v[152:155], v[8:9], off
	global_load_dword v207, v157, s[28:29]
	global_load_dword v206, v[10:11], off
	s_setprio 3
	s_waitcnt vmcnt(25)
	v_lshlrev_b32_e32 v8, 7, v148
	v_and_b32_e32 v156, 0x7fff80, v8
	v_lshl_add_u64 v[8:9], v[180:181], 0, v[156:157]
	v_lshlrev_b32_sdwa v156, v194, v148 dst_sel:DWORD dst_unused:UNUSED_PAD src0_sel:DWORD src1_sel:WORD_1
	v_lshl_add_u64 v[10:11], v[180:181], 0, v[156:157]
	global_load_dwordx4 v[48:51], v[8:9], off
	global_load_dwordx4 v[52:55], v[10:11], off
	v_lshlrev_b32_e32 v8, 7, v149
	v_and_b32_e32 v156, 0x7fff80, v8
	v_lshl_add_u64 v[8:9], v[180:181], 0, v[156:157]
	v_lshlrev_b32_sdwa v156, v194, v149 dst_sel:DWORD dst_unused:UNUSED_PAD src0_sel:DWORD src1_sel:WORD_1
	v_lshl_add_u64 v[10:11], v[180:181], 0, v[156:157]
	global_load_dwordx4 v[68:71], v[8:9], off
	global_load_dwordx4 v[72:75], v[10:11], off
	v_lshlrev_b32_e32 v8, 7, v150
	v_and_b32_e32 v156, 0x7fff80, v8
	v_lshl_add_u64 v[8:9], v[180:181], 0, v[156:157]
	v_lshlrev_b32_sdwa v156, v194, v150 dst_sel:DWORD dst_unused:UNUSED_PAD src0_sel:DWORD src1_sel:WORD_1
	v_lshl_add_u64 v[10:11], v[180:181], 0, v[156:157]
	global_load_dwordx4 v[32:35], v[8:9], off
	global_load_dwordx4 v[36:39], v[10:11], off
	v_lshlrev_b32_e32 v8, 7, v151
	v_and_b32_e32 v156, 0x7fff80, v8
	v_lshl_add_u64 v[8:9], v[180:181], 0, v[156:157]
	v_lshlrev_b32_sdwa v156, v194, v151 dst_sel:DWORD dst_unused:UNUSED_PAD src0_sel:DWORD src1_sel:WORD_1
	v_lshl_add_u64 v[10:11], v[180:181], 0, v[156:157]
	global_load_dwordx4 v[56:59], v[8:9], off
	global_load_dwordx4 v[60:63], v[10:11], off
	v_lshlrev_b32_e32 v8, 7, v144
	v_and_b32_e32 v156, 0x7fff80, v8
	v_lshl_add_u64 v[8:9], v[180:181], 0, v[156:157]
	v_lshlrev_b32_sdwa v156, v194, v144 dst_sel:DWORD dst_unused:UNUSED_PAD src0_sel:DWORD src1_sel:WORD_1
	v_lshl_add_u64 v[10:11], v[180:181], 0, v[156:157]
	global_load_dwordx4 v[16:19], v[8:9], off
	global_load_dwordx4 v[20:23], v[10:11], off
	v_lshlrev_b32_e32 v8, 7, v145
	v_and_b32_e32 v156, 0x7fff80, v8
	v_lshl_add_u64 v[8:9], v[180:181], 0, v[156:157]
	v_lshlrev_b32_sdwa v156, v194, v145 dst_sel:DWORD dst_unused:UNUSED_PAD src0_sel:DWORD src1_sel:WORD_1
	v_lshl_add_u64 v[10:11], v[180:181], 0, v[156:157]
	global_load_dwordx4 v[40:43], v[8:9], off
	global_load_dwordx4 v[44:47], v[10:11], off
	v_lshlrev_b32_e32 v8, 7, v146
	v_and_b32_e32 v156, 0x7fff80, v8
	v_lshl_add_u64 v[8:9], v[180:181], 0, v[156:157]
	v_lshlrev_b32_sdwa v156, v194, v146 dst_sel:DWORD dst_unused:UNUSED_PAD src0_sel:DWORD src1_sel:WORD_1
	v_lshlrev_b32_e32 v24, 7, v147
	v_lshl_add_u64 v[12:13], v[180:181], 0, v[156:157]
	v_and_b32_e32 v156, 0x7fff80, v24
	v_lshl_add_u64 v[24:25], v[180:181], 0, v[156:157]
	v_lshlrev_b32_sdwa v156, v194, v147 dst_sel:DWORD dst_unused:UNUSED_PAD src0_sel:DWORD src1_sel:WORD_1
	v_lshl_add_u64 v[28:29], v[180:181], 0, v[156:157]
	global_load_dwordx4 v[8:11], v[8:9], off
	s_nop 0
	global_load_dwordx4 v[12:15], v[12:13], off
	s_nop 0
	global_load_dwordx4 v[24:27], v[24:25], off
	s_nop 0
	global_load_dwordx4 v[28:31], v[28:29], off
	s_setprio 0
	v_mov_b32_dpp v230, v4 row_ror:8 row_mask:0xf bank_mask:0xf
	v_cndmask_b32_e64 v220, v230, v4, s[40:41]
	v_cndmask_b32_e64 v224, v4, v230, s[40:41]
	v_mov_b32_dpp v230, v5 row_ror:8 row_mask:0xf bank_mask:0xf
	v_cndmask_b32_e64 v221, v230, v5, s[40:41]
	v_cndmask_b32_e64 v225, v5, v230, s[40:41]
	v_mov_b32_dpp v230, v6 row_ror:8 row_mask:0xf bank_mask:0xf
	v_cndmask_b32_e64 v222, v230, v6, s[40:41]
	v_cndmask_b32_e64 v226, v6, v230, s[40:41]
	v_mov_b32_dpp v230, v7 row_ror:8 row_mask:0xf bank_mask:0xf
	v_cndmask_b32_e64 v223, v230, v7, s[40:41]
	v_cndmask_b32_e64 v227, v7, v230, s[40:41]
	s_waitcnt vmcnt(34)
	ds_write_b128 v208, v[128:131]
	ds_write_b128 v209, v[132:135] offset:1024
	ds_write_b128 v210, v[136:139] offset:2048
	ds_write_b128 v211, v[140:143] offset:3072
	ds_read_b64_tr_b8 v[240:241], v212
	ds_read_b64_tr_b8 v[242:243], v213
	ds_read_b64_tr_b8 v[244:245], v214
	ds_read_b64_tr_b8 v[246:247], v215
	ds_read_b64_tr_b8 v[248:249], v216
	ds_read_b64_tr_b8 v[250:251], v217
	ds_read_b64_tr_b8 v[252:253], v218
	ds_read_b64_tr_b8 v[228:229], v219
	s_waitcnt lgkmcnt(4)
	s_waitcnt vmcnt(30)
	ds_write_b128 v208, v[112:115] offset:4096
	ds_write_b128 v209, v[116:119] offset:5120
	ds_write_b128 v210, v[120:123] offset:6144
	ds_write_b128 v211, v[124:127] offset:7168
	ds_read_b64_tr_b8 v[128:129], v212 offset:4096
	ds_read_b64_tr_b8 v[130:131], v213 offset:4096
	ds_read_b64_tr_b8 v[132:133], v214 offset:4096
	ds_read_b64_tr_b8 v[134:135], v215 offset:4096
	v_dot4_i32_i8 v232, v240, v220, 0
	v_dot4_i32_i8 v233, v242, v220, 0
	v_dot4_i32_i8 v234, v244, v220, 0
	v_dot4_i32_i8 v235, v246, v220, 0
	v_dot4_i32_i8 v232, v241, v224, v232
	v_dot4_i32_i8 v233, v243, v224, v233
	v_dot4_i32_i8 v234, v245, v224, v234
	v_dot4_i32_i8 v235, v247, v224, v235
	s_waitcnt lgkmcnt(8)
	ds_read_b64_tr_b8 v[240:241], v216 offset:4096
	ds_read_b64_tr_b8 v[242:243], v217 offset:4096
	ds_read_b64_tr_b8 v[244:245], v218 offset:4096
	ds_read_b64_tr_b8 v[246:247], v219 offset:4096
	v_dot4_i32_i8 v236, v248, v220, 0
	v_dot4_i32_i8 v237, v250, v220, 0
	v_dot4_i32_i8 v238, v252, v220, 0
	v_dot4_i32_i8 v239, v228, v220, 0
	v_dot4_i32_i8 v236, v249, v224, v236
	v_dot4_i32_i8 v237, v251, v224, v237
	v_dot4_i32_i8 v238, v253, v224, v238
	v_dot4_i32_i8 v239, v229, v224, v239
	s_waitcnt lgkmcnt(4)
	s_waitcnt vmcnt(26)
	ds_write_b128 v208, v[96:99] offset:8192
	ds_write_b128 v209, v[100:103] offset:9216
	ds_write_b128 v210, v[104:107] offset:10240
	ds_write_b128 v211, v[108:111] offset:11264
	ds_read_b64_tr_b8 v[248:249], v212 offset:8192
	ds_read_b64_tr_b8 v[250:251], v213 offset:8192
	ds_read_b64_tr_b8 v[252:253], v214 offset:8192
	ds_read_b64_tr_b8 v[228:229], v215 offset:8192
	v_dot4_i32_i8 v232, v128, v221, v232
	v_dot4_i32_i8 v233, v130, v221, v233
	v_dot4_i32_i8 v234, v132, v221, v234
	v_dot4_i32_i8 v235, v134, v221, v235
	v_dot4_i32_i8 v232, v129, v225, v232
	v_dot4_i32_i8 v233, v131, v225, v233
	v_dot4_i32_i8 v234, v133, v225, v234
	v_dot4_i32_i8 v235, v135, v225, v235
	s_waitcnt lgkmcnt(8)
	ds_read_b64_tr_b8 v[128:129], v216 offset:8192
	ds_read_b64_tr_b8 v[130:131], v217 offset:8192
	ds_read_b64_tr_b8 v[132:133], v218 offset:8192
	ds_read_b64_tr_b8 v[134:135], v219 offset:8192
	v_dot4_i32_i8 v236, v240, v221, v236
	v_dot4_i32_i8 v237, v242, v221, v237
	v_dot4_i32_i8 v238, v244, v221, v238
	v_dot4_i32_i8 v239, v246, v221, v239
	v_dot4_i32_i8 v236, v241, v225, v236
	v_dot4_i32_i8 v237, v243, v225, v237
	v_dot4_i32_i8 v238, v245, v225, v238
	v_dot4_i32_i8 v239, v247, v225, v239
	s_waitcnt lgkmcnt(4)
	s_waitcnt vmcnt(22)
	ds_write_b128 v208, v[80:83] offset:12288
	ds_write_b128 v209, v[84:87] offset:13312
	ds_write_b128 v210, v[88:91] offset:14336
	ds_write_b128 v211, v[92:95] offset:15360
	ds_read_b64_tr_b8 v[240:241], v212 offset:12288
	ds_read_b64_tr_b8 v[242:243], v213 offset:12288
	ds_read_b64_tr_b8 v[244:245], v214 offset:12288
	ds_read_b64_tr_b8 v[246:247], v215 offset:12288
	v_dot4_i32_i8 v232, v248, v222, v232
	v_dot4_i32_i8 v233, v250, v222, v233
	v_dot4_i32_i8 v234, v252, v222, v234
	v_dot4_i32_i8 v235, v228, v222, v235
	v_dot4_i32_i8 v232, v249, v226, v232
	v_dot4_i32_i8 v233, v251, v226, v233
	v_dot4_i32_i8 v234, v253, v226, v234
	v_dot4_i32_i8 v235, v229, v226, v235
	s_waitcnt lgkmcnt(8)
	ds_read_b64_tr_b8 v[248:249], v216 offset:12288
	ds_read_b64_tr_b8 v[250:251], v217 offset:12288
	ds_read_b64_tr_b8 v[252:253], v218 offset:12288
	ds_read_b64_tr_b8 v[228:229], v219 offset:12288
	v_dot4_i32_i8 v236, v128, v222, v236
	v_dot4_i32_i8 v237, v130, v222, v237
	v_dot4_i32_i8 v238, v132, v222, v238
	v_dot4_i32_i8 v239, v134, v222, v239
	v_dot4_i32_i8 v236, v129, v226, v236
	v_dot4_i32_i8 v237, v131, v226, v237
	v_dot4_i32_i8 v238, v133, v226, v238
	v_dot4_i32_i8 v239, v135, v226, v239
	s_waitcnt lgkmcnt(4)
	v_dot4_i32_i8 v232, v240, v223, v232
	v_dot4_i32_i8 v233, v242, v223, v233
	v_dot4_i32_i8 v234, v244, v223, v234
	v_dot4_i32_i8 v235, v246, v223, v235
	v_dot4_i32_i8 v232, v241, v227, v232
	v_dot4_i32_i8 v233, v243, v227, v233
	v_dot4_i32_i8 v234, v245, v227, v234
	v_dot4_i32_i8 v235, v247, v227, v235
	s_waitcnt lgkmcnt(0)
	v_dot4_i32_i8 v236, v248, v223, v236
	v_dot4_i32_i8 v237, v250, v223, v237
	v_dot4_i32_i8 v238, v252, v223, v238
	v_dot4_i32_i8 v239, v228, v223, v239
	v_dot4_i32_i8 v236, v249, v227, v236
	v_dot4_i32_i8 v237, v251, v227, v237
	v_dot4_i32_i8 v238, v253, v227, v238
	v_dot4_i32_i8 v239, v229, v227, v239
	s_nop 2
	v_permlane32_swap_b32_e32 v232, v236
	v_permlane32_swap_b32_e32 v233, v237
	v_permlane32_swap_b32_e32 v234, v238
	v_permlane32_swap_b32_e32 v235, v239
	v_add_u32_e32 v232, v232, v236
	v_add_u32_e32 v233, v233, v237
	v_add_u32_e32 v234, v234, v238
	v_add_u32_e32 v235, v235, v239
	s_nop 1
	v_permlane16_swap_b32_e32 v232, v234
	v_permlane16_swap_b32_e32 v233, v235
	v_add_u32_e32 v232, v232, v234
	v_add_u32_e32 v233, v233, v235
	s_nop 1
	v_mov_b32_dpp v234, v232 quad_perm:[1,0,3,2] row_mask:0xf bank_mask:0xf
	v_mov_b32_dpp v235, v233 quad_perm:[1,0,3,2] row_mask:0xf bank_mask:0xf
	v_cndmask_b32_e64 v236, v235, v232, s[44:45]
	v_cndmask_b32_e64 v237, v233, v234, s[44:45]
	v_cvt_f32_i32_e32 v236, v236
	v_cvt_f32_i32_e32 v237, v237
	v_lshlrev_b32_e32 v4, 16, v199
	v_and_b32_e32 v5, 0xffff0000, v199
	v_fmac_f32_e32 v4, v198, v236
	v_fmac_f32_e32 v5, v198, v237
	v_mul_f32_e32 v6, v5, v5
	v_fmac_f32_e32 v6, v4, v4
	s_nop 1
	v_add_f32_dpp v6, v6, v6 quad_perm:[1,0,3,2] row_mask:0xf bank_mask:0xf
	s_nop 1
	v_add_f32_dpp v6, v6, v6 quad_perm:[2,3,0,1] row_mask:0xf bank_mask:0xf
	s_nop 1
	v_add_f32_dpp v6, v6, v6 row_half_mirror row_mask:0xf bank_mask:0xf
	s_nop 1
	v_add_f32_dpp v6, v6, v6 row_mirror row_mask:0xf bank_mask:0xf
	v_mov_b32_e32 v7, v6
	s_nop 1
	v_permlane16_swap_b32_e32 v6, v7
	v_add_f32_e32 v6, v6, v7
	v_mov_b32_e32 v7, v6
	s_nop 1
	v_permlane32_swap_b32_e32 v6, v7
	v_add_f32_e32 v6, v6, v7
	s_add_i32 s18, s23, s20
	s_cmpk_gt_i32 s18, 0x5fff
	s_cbranch_scc1 .LBB0_1088
	s_ashr_i32 s19, s18, 31
	s_lshl_b64 s[20:21], s[18:19], 12
	v_lshl_add_u64 v[80:81], v[182:183], 0, s[20:21]
	v_cvt_pk_bf16_f32 v4, v4, v5
	global_store_dword v[80:81], v4, off
	s_and_saveexec_b64 s[20:21], s[42:43]
	s_cbranch_execz .LBB0_1087
	s_lshl_b64 s[18:19], s[18:19], 6
	v_lshl_add_u64 v[4:5], v[184:185], 0, s[18:19]
	global_store_dword v[4:5], v6, off
	s_branch .LBB0_1087
